# attention: waves 4-7 keep the static priority raise, but the late entry (s_sleep 8) moves to the older half (waves 0-3)
# speedup vs baseline: 1.0092x; 1.0017x over previous
; #define PROBE_BEGIN(id) unsigned long long pb_t0_##id = 0; if (PROBE_SEC == (id)) pb_t0_##id = __builtin_amdgcn_s_memrealtime();
; #define LAS __attribute__((address_space(3)))
; __device__ __forceinline__ void attn_compute(Frame& F, int id) {
;     const int b = id >> 5, n = (id >> 1) & 15, kvh = id & 1;
;     LAS unsigned char* lds = F.lds;
;     const bf16* Q = (const bf16*)(F.ws + WS_Q); const bf16* ZA = (const bf16*)(F.ws + WS_ZA);
;     bf16* A5 = (bf16*)(F.ws + WS_A5);
;     const float* sink = F.in[4];
;     const int lane = F.lane, wid = F.wave;
;     const int key0 = 128 * (n - 1);
;     PROBE_BEGIN(4)
;     const int g = wid >> 1, qh = wid & 1, h = kvh * 4 + g, r = lane & 31, hh = lane >> 5;
;     const float sk = sink[h] * LOG2E;
;     const size_t tok0 = (size_t)b * SEQ + 128 * n + 64 * qh + r;
;     bf16x8 qf[2][4];
; #pragma unroll
;     for (int qb = 0; qb < 2; ++qb)
; #pragma unroll
;         for (int st = 0; st < 4; ++st) qf[qb][st] = *(const bf16x8*)(Q + (tok0 + 32 * qb) * 512 + h * 64 + 16 * st + 8 * hh);
;     const LAS f32x4* BT4 = (const LAS f32x4*)(lds + OFF_B);
;     const int ktA = 2 * qh;
;     const LAS f32x4* BTg = BT4 + g * NBT + 63 - r + 4 * hh;
;     const LAS unsigned char* kbase = lds + OFF_K + (32 * ktA + r) * KROW + 16 * hh;
;     const LAS unsigned char* vbase = lds + OFF_V + r * VROW + (32 * ktA + 4 * hh) * 2;
;     float m0 = sk, m1 = sk, l0 = 0.f, l1 = 0.f;
;     f32x16 O0[2], O1[2];
; #pragma unroll
;     for (int q = 0; q < 16; ++q) { O0[0][q] = 0.f; O0[1][q] = 0.f; O1[0][q] = 0.f; O1[1][q] = 0.f; }
; #pragma unroll 1
;     for (int j = 0; j < 9; ++j) {
;         const int p0 = key0 + 32 * (ktA + j), p1 = p0 + 32;
.LBB0_574:
	v_readfirstlane_b32 s4, v0
	s_nop 3
	s_bitcmp1_b32 s4, 8
	s_cbranch_scc0 .Lattn_lo_half
	s_setprio 1
	s_branch .Lattn_hi_done
.Lattn_lo_half:
	s_sleep 8
